# gu_barx
# speedup vs baseline: 1.0055x; 1.0055x over previous
; __device__ __forceinline__ float silu_f(float x) { return x * __builtin_amdgcn_rcpf(1.f + __builtin_amdgcn_exp2f(-1.4426950408889634f * x)); }
; template <int EPI>
; __device__ __forceinline__ void gemm_epi(const GemmArgs& G, const f32x4 (&a)[4][2], int rbase, int cbase, int fq, const float (&ssv)[4]) {
;   const int tn = cbase >> 8;
; #pragma unroll
;   for (int m = 0; m < 4; ++m) {
;     const int row = rbase + m * 16;
;     float rs = 1.f;
;     if constexpr (EPI == EPI_GU || EPI == EPI_EVIN || EPI == EPI_ODIN) rs = rsqrtf(ssv[m] * (1.f / 2048.f) + 1e-6f);
;     if constexpr (EPI == EPI_GU) {
;       const f32x4 gv = a[m][0] * rs, uv = a[m][1] * rs;
;       const int hc = (cbase >> 1) + fq * 4;
;       u32x2 o = {cvtpk(silu_f(gv[0]) * uv[0], silu_f(gv[1]) * uv[1]), cvtpk(silu_f(gv[2]) * uv[2], silu_f(gv[3]) * uv[3])};
;       *reinterpret_cast<u32x2*>(G.d0 + (size_t)(row - G.row0) * DFF + hc) = o;
.LBB0_2558:
	v_readfirstlane_b32 s16, v224
	s_andn2_b32 s16, s16, 63
	s_nop 0
	v_add_u32_e32 v128, s16, v225
	v_mov_b32_e32 v158, 0xbfb8aa3b
	v_and_b32_e32 v129, 15, v128
	v_ashrrev_i32_e32 v135, 2, v128
	v_and_or_b32 v129, v135, 64, v129
	v_lshrrev_b32_e32 v135, 1, v128
	v_and_b32_e32 v135, 0x60, v135
	v_or_b32_e32 v136, s29, v135
	v_lshrrev_b32_e32 v128, 2, v128
	v_ashrrev_i32_e32 v140, 1, v136
	v_and_b32_e32 v136, 12, v128
	v_or_b32_e32 v140, v140, v136
	v_add_u32_e32 v144, s28, v129
	v_subrev_u32_e32 v141, s40, v144
	v_mul_u32_u24_e32 v141, 0x2c00, v141
	v_lshl_add_u32 v141, v140, 1, v141
	v_mov_b32_e32 v160, 1.0
	s_waitcnt vmcnt(8)
	v_fmamk_f32 v162, v139, 0x3a000000, v229
	v_fmamk_f32 v164, v138, 0x3a000000, v229
	v_fmamk_f32 v166, v137, 0x3a000000, v229
	v_fmamk_f32 v168, v134, 0x3a000000, v229
	v_fmamk_f32 v170, v133, 0x3a000000, v229
	v_fmamk_f32 v172, v132, 0x3a000000, v229
	v_fmamk_f32 v174, v131, 0x3a000000, v229
	v_fmamk_f32 v176, v130, 0x3a000000, v229
	v_rsq_f32_e32 v162, v162
	v_rsq_f32_e32 v164, v164
	v_rsq_f32_e32 v166, v166
	v_rsq_f32_e32 v168, v168
	v_rsq_f32_e32 v170, v170
	v_rsq_f32_e32 v172, v172
	v_rsq_f32_e32 v174, v174
	v_rsq_f32_e32 v176, v176
	v_pk_mul_f32 v[120:121], v[162:163], v[120:121] op_sel_hi:[0,1]
	v_pk_mul_f32 v[112:113], v[164:165], v[112:113] op_sel_hi:[0,1]
	v_pk_mul_f32 v[122:123], v[162:163], v[122:123] op_sel_hi:[0,1]
	v_pk_mul_f32 v[114:115], v[164:165], v[114:115] op_sel_hi:[0,1]
	v_pk_mul_f32 v[124:125], v[162:163], v[124:125] op_sel_hi:[0,1]
	v_pk_mul_f32 v[116:117], v[164:165], v[116:117] op_sel_hi:[0,1]
	v_pk_mul_f32 v[126:127], v[162:163], v[126:127] op_sel_hi:[0,1]
	v_pk_mul_f32 v[118:119], v[164:165], v[118:119] op_sel_hi:[0,1]
	v_pk_mul_f32 v[182:183], v[158:159], v[120:121] op_sel_hi:[0,1]
	v_pk_mul_f32 v[186:187], v[158:159], v[112:113] op_sel_hi:[0,1]
	v_pk_mul_f32 v[184:185], v[158:159], v[122:123] op_sel_hi:[0,1]
	v_pk_mul_f32 v[188:189], v[158:159], v[114:115] op_sel_hi:[0,1]
	v_exp_f32_e32 v182, v182
	v_exp_f32_e32 v186, v186
	v_exp_f32_e32 v183, v183
	v_exp_f32_e32 v187, v187
	v_exp_f32_e32 v184, v184
	v_exp_f32_e32 v188, v188
	v_exp_f32_e32 v185, v185
	v_exp_f32_e32 v189, v189
	v_pk_add_f32 v[182:183], v[160:161], v[182:183] op_sel_hi:[0,1]
	v_pk_add_f32 v[186:187], v[160:161], v[186:187] op_sel_hi:[0,1]
	v_pk_add_f32 v[184:185], v[160:161], v[184:185] op_sel_hi:[0,1]
	v_pk_add_f32 v[188:189], v[160:161], v[188:189] op_sel_hi:[0,1]
	v_rcp_f32_e32 v182, v182
	v_rcp_f32_e32 v186, v186
	v_rcp_f32_e32 v183, v183
	v_rcp_f32_e32 v187, v187
	v_rcp_f32_e32 v184, v184
	v_rcp_f32_e32 v188, v188
	v_rcp_f32_e32 v185, v185
	v_rcp_f32_e32 v189, v189
	v_pk_mul_f32 v[120:121], v[120:121], v[182:183]
	v_pk_mul_f32 v[112:113], v[112:113], v[186:187]
	v_pk_mul_f32 v[122:123], v[122:123], v[184:185]
	v_pk_mul_f32 v[114:115], v[114:115], v[188:189]
	v_pk_mul_f32 v[120:121], v[124:125], v[120:121]
	v_pk_mul_f32 v[112:113], v[116:117], v[112:113]
	v_pk_mul_f32 v[122:123], v[126:127], v[122:123]
	v_pk_mul_f32 v[114:115], v[118:119], v[114:115]
	v_cvt_pk_bf16_f32 v200, v120, v121
	v_cvt_pk_bf16_f32 v202, v112, v113
	v_cvt_pk_bf16_f32 v201, v122, v123
	v_cvt_pk_bf16_f32 v203, v114, v115
	v_mov_b32_e32 v210, v141
	v_add_u32_e32 v211, 0x2c000, v141
	global_store_dwordx2 v210, v[200:201], s[10:11]
	global_store_dwordx2 v211, v[202:203], s[10:11]
	v_pk_mul_f32 v[104:105], v[166:167], v[104:105] op_sel_hi:[0,1]
	v_pk_mul_f32 v[96:97], v[168:169], v[96:97] op_sel_hi:[0,1]
	v_pk_mul_f32 v[106:107], v[166:167], v[106:107] op_sel_hi:[0,1]
	v_pk_mul_f32 v[98:99], v[168:169], v[98:99] op_sel_hi:[0,1]
	v_pk_mul_f32 v[108:109], v[166:167], v[108:109] op_sel_hi:[0,1]
	v_pk_mul_f32 v[100:101], v[168:169], v[100:101] op_sel_hi:[0,1]
	v_pk_mul_f32 v[110:111], v[166:167], v[110:111] op_sel_hi:[0,1]
	v_pk_mul_f32 v[102:103], v[168:169], v[102:103] op_sel_hi:[0,1]
	v_pk_mul_f32 v[190:191], v[158:159], v[104:105] op_sel_hi:[0,1]
	v_pk_mul_f32 v[194:195], v[158:159], v[96:97] op_sel_hi:[0,1]
	v_pk_mul_f32 v[192:193], v[158:159], v[106:107] op_sel_hi:[0,1]
	v_pk_mul_f32 v[196:197], v[158:159], v[98:99] op_sel_hi:[0,1]
	v_exp_f32_e32 v190, v190
	v_exp_f32_e32 v194, v194
	v_exp_f32_e32 v191, v191
	v_exp_f32_e32 v195, v195
	v_exp_f32_e32 v192, v192
	v_exp_f32_e32 v196, v196
	v_exp_f32_e32 v193, v193
	v_exp_f32_e32 v197, v197
	v_pk_add_f32 v[190:191], v[160:161], v[190:191] op_sel_hi:[0,1]
	v_pk_add_f32 v[194:195], v[160:161], v[194:195] op_sel_hi:[0,1]
	v_pk_add_f32 v[192:193], v[160:161], v[192:193] op_sel_hi:[0,1]
	v_pk_add_f32 v[196:197], v[160:161], v[196:197] op_sel_hi:[0,1]
	v_rcp_f32_e32 v190, v190
	v_rcp_f32_e32 v194, v194
	v_rcp_f32_e32 v191, v191
	v_rcp_f32_e32 v195, v195
	v_rcp_f32_e32 v192, v192
	v_rcp_f32_e32 v196, v196
	v_rcp_f32_e32 v193, v193
	v_rcp_f32_e32 v197, v197
	v_pk_mul_f32 v[104:105], v[104:105], v[190:191]
	v_pk_mul_f32 v[96:97], v[96:97], v[194:195]
	v_pk_mul_f32 v[106:107], v[106:107], v[192:193]
	v_pk_mul_f32 v[98:99], v[98:99], v[196:197]
	v_pk_mul_f32 v[104:105], v[108:109], v[104:105]
	v_pk_mul_f32 v[96:97], v[100:101], v[96:97]
	v_pk_mul_f32 v[106:107], v[110:111], v[106:107]
	v_pk_mul_f32 v[98:99], v[102:103], v[98:99]
	v_cvt_pk_bf16_f32 v204, v104, v105
	v_cvt_pk_bf16_f32 v206, v96, v97
	v_cvt_pk_bf16_f32 v205, v106, v107
	v_cvt_pk_bf16_f32 v207, v98, v99
	v_add_u32_e32 v212, 0x58000, v141
	v_add_u32_e32 v213, 0x84000, v141
	global_store_dwordx2 v212, v[204:205], s[10:11]
	global_store_dwordx2 v213, v[206:207], s[10:11]
	v_pk_mul_f32 v[88:89], v[162:163], v[88:89] op_sel_hi:[0,1]
	v_pk_mul_f32 v[80:81], v[164:165], v[80:81] op_sel_hi:[0,1]
	v_pk_mul_f32 v[90:91], v[162:163], v[90:91] op_sel_hi:[0,1]
; __device__ __forceinline__ float silu_f(float x) { return x * __builtin_amdgcn_rcpf(1.f + __builtin_amdgcn_exp2f(-1.4426950408889634f * x)); }
; template <int EPI>
; __device__ __forceinline__ void gemm_epi(const GemmArgs& G, const f32x4 (&a)[4][2], int rbase, int cbase, int fq, const float (&ssv)[4]) {
;   const int tn = cbase >> 8;
; #pragma unroll
;   for (int m = 0; m < 4; ++m) {
;     const int row = rbase + m * 16;
;     float rs = 1.f;
;     if constexpr (EPI == EPI_GU || EPI == EPI_EVIN || EPI == EPI_ODIN) rs = rsqrtf(ssv[m] * (1.f / 2048.f) + 1e-6f);
;     if constexpr (EPI == EPI_GU) {
;       const f32x4 gv = a[m][0] * rs, uv = a[m][1] * rs;
;       const int hc = (cbase >> 1) + fq * 4;
;       u32x2 o = {cvtpk(silu_f(gv[0]) * uv[0], silu_f(gv[1]) * uv[1]), cvtpk(silu_f(gv[2]) * uv[2], silu_f(gv[3]) * uv[3])};
;       *reinterpret_cast<u32x2*>(G.d0 + (size_t)(row - G.row0) * DFF + hc) = o;
	v_pk_mul_f32 v[82:83], v[164:165], v[82:83] op_sel_hi:[0,1]
	v_pk_mul_f32 v[92:93], v[162:163], v[92:93] op_sel_hi:[0,1]
	v_pk_mul_f32 v[84:85], v[164:165], v[84:85] op_sel_hi:[0,1]
	v_pk_mul_f32 v[94:95], v[162:163], v[94:95] op_sel_hi:[0,1]
	v_pk_mul_f32 v[86:87], v[164:165], v[86:87] op_sel_hi:[0,1]
	v_pk_mul_f32 v[182:183], v[158:159], v[88:89] op_sel_hi:[0,1]
	v_pk_mul_f32 v[186:187], v[158:159], v[80:81] op_sel_hi:[0,1]
	v_pk_mul_f32 v[184:185], v[158:159], v[90:91] op_sel_hi:[0,1]
	v_pk_mul_f32 v[188:189], v[158:159], v[82:83] op_sel_hi:[0,1]
	v_exp_f32_e32 v182, v182
	v_exp_f32_e32 v186, v186
	v_exp_f32_e32 v183, v183
	v_exp_f32_e32 v187, v187
	v_exp_f32_e32 v184, v184
	v_exp_f32_e32 v188, v188
	v_exp_f32_e32 v185, v185
	v_exp_f32_e32 v189, v189
	v_pk_add_f32 v[182:183], v[160:161], v[182:183] op_sel_hi:[0,1]
	v_pk_add_f32 v[186:187], v[160:161], v[186:187] op_sel_hi:[0,1]
	v_pk_add_f32 v[184:185], v[160:161], v[184:185] op_sel_hi:[0,1]
	v_pk_add_f32 v[188:189], v[160:161], v[188:189] op_sel_hi:[0,1]
	v_rcp_f32_e32 v182, v182
	v_rcp_f32_e32 v186, v186
	v_rcp_f32_e32 v183, v183
	v_rcp_f32_e32 v187, v187
	v_rcp_f32_e32 v184, v184
	v_rcp_f32_e32 v188, v188
	v_rcp_f32_e32 v185, v185
	v_rcp_f32_e32 v189, v189
	v_pk_mul_f32 v[88:89], v[88:89], v[182:183]
	v_pk_mul_f32 v[80:81], v[80:81], v[186:187]
	v_pk_mul_f32 v[90:91], v[90:91], v[184:185]
	v_pk_mul_f32 v[82:83], v[82:83], v[188:189]
	v_pk_mul_f32 v[88:89], v[92:93], v[88:89]
	v_pk_mul_f32 v[80:81], v[84:85], v[80:81]
	v_pk_mul_f32 v[90:91], v[94:95], v[90:91]
	v_pk_mul_f32 v[82:83], v[86:87], v[82:83]
	v_cvt_pk_bf16_f32 v200, v88, v89
	v_cvt_pk_bf16_f32 v202, v80, v81
	v_cvt_pk_bf16_f32 v201, v90, v91
	v_cvt_pk_bf16_f32 v203, v82, v83
	v_add_u32_e32 v210, 0x80, v141
	v_add_u32_e32 v211, 0x2c080, v141
	global_store_dwordx2 v210, v[200:201], s[10:11]
	global_store_dwordx2 v211, v[202:203], s[10:11]
	v_pk_mul_f32 v[72:73], v[166:167], v[72:73] op_sel_hi:[0,1]
	v_pk_mul_f32 v[64:65], v[168:169], v[64:65] op_sel_hi:[0,1]
	v_pk_mul_f32 v[74:75], v[166:167], v[74:75] op_sel_hi:[0,1]
	v_pk_mul_f32 v[66:67], v[168:169], v[66:67] op_sel_hi:[0,1]
	v_pk_mul_f32 v[76:77], v[166:167], v[76:77] op_sel_hi:[0,1]
	v_pk_mul_f32 v[68:69], v[168:169], v[68:69] op_sel_hi:[0,1]
	v_pk_mul_f32 v[78:79], v[166:167], v[78:79] op_sel_hi:[0,1]
	v_pk_mul_f32 v[70:71], v[168:169], v[70:71] op_sel_hi:[0,1]
	v_pk_mul_f32 v[190:191], v[158:159], v[72:73] op_sel_hi:[0,1]
	v_pk_mul_f32 v[194:195], v[158:159], v[64:65] op_sel_hi:[0,1]
	v_pk_mul_f32 v[192:193], v[158:159], v[74:75] op_sel_hi:[0,1]
	v_pk_mul_f32 v[196:197], v[158:159], v[66:67] op_sel_hi:[0,1]
	v_exp_f32_e32 v190, v190
	v_exp_f32_e32 v194, v194
	v_exp_f32_e32 v191, v191
	v_exp_f32_e32 v195, v195
	v_exp_f32_e32 v192, v192
	v_exp_f32_e32 v196, v196
	v_exp_f32_e32 v193, v193
	v_exp_f32_e32 v197, v197
	v_pk_add_f32 v[190:191], v[160:161], v[190:191] op_sel_hi:[0,1]
	v_pk_add_f32 v[194:195], v[160:161], v[194:195] op_sel_hi:[0,1]
	v_pk_add_f32 v[192:193], v[160:161], v[192:193] op_sel_hi:[0,1]
	v_pk_add_f32 v[196:197], v[160:161], v[196:197] op_sel_hi:[0,1]
	v_rcp_f32_e32 v190, v190
	v_rcp_f32_e32 v194, v194
	v_rcp_f32_e32 v191, v191
	v_rcp_f32_e32 v195, v195
	v_rcp_f32_e32 v192, v192
	v_rcp_f32_e32 v196, v196
	v_rcp_f32_e32 v193, v193
	v_rcp_f32_e32 v197, v197
	v_pk_mul_f32 v[72:73], v[72:73], v[190:191]
	v_pk_mul_f32 v[64:65], v[64:65], v[194:195]
	v_pk_mul_f32 v[74:75], v[74:75], v[192:193]
	v_pk_mul_f32 v[66:67], v[66:67], v[196:197]
	v_pk_mul_f32 v[72:73], v[76:77], v[72:73]
	v_pk_mul_f32 v[64:65], v[68:69], v[64:65]
	v_pk_mul_f32 v[74:75], v[78:79], v[74:75]
	v_pk_mul_f32 v[66:67], v[70:71], v[66:67]
	v_cvt_pk_bf16_f32 v204, v72, v73
	v_cvt_pk_bf16_f32 v206, v64, v65
	v_cvt_pk_bf16_f32 v205, v74, v75
	v_cvt_pk_bf16_f32 v207, v66, v67
	v_add_u32_e32 v212, 0x58080, v141
	v_add_u32_e32 v213, 0x84080, v141
	global_store_dwordx2 v212, v[204:205], s[10:11]
	global_store_dwordx2 v213, v[206:207], s[10:11]
	v_pk_mul_f32 v[56:57], v[170:171], v[56:57] op_sel_hi:[0,1]
	v_pk_mul_f32 v[48:49], v[172:173], v[48:49] op_sel_hi:[0,1]
	v_pk_mul_f32 v[58:59], v[170:171], v[58:59] op_sel_hi:[0,1]
	v_pk_mul_f32 v[50:51], v[172:173], v[50:51] op_sel_hi:[0,1]
	v_pk_mul_f32 v[60:61], v[170:171], v[60:61] op_sel_hi:[0,1]
	v_pk_mul_f32 v[52:53], v[172:173], v[52:53] op_sel_hi:[0,1]
	v_pk_mul_f32 v[62:63], v[170:171], v[62:63] op_sel_hi:[0,1]
	v_pk_mul_f32 v[54:55], v[172:173], v[54:55] op_sel_hi:[0,1]
	v_pk_mul_f32 v[182:183], v[158:159], v[56:57] op_sel_hi:[0,1]
	v_pk_mul_f32 v[186:187], v[158:159], v[48:49] op_sel_hi:[0,1]
	v_pk_mul_f32 v[184:185], v[158:159], v[58:59] op_sel_hi:[0,1]
	v_pk_mul_f32 v[188:189], v[158:159], v[50:51] op_sel_hi:[0,1]
	v_exp_f32_e32 v182, v182
	v_exp_f32_e32 v186, v186
	v_exp_f32_e32 v183, v183
	v_exp_f32_e32 v187, v187
	v_exp_f32_e32 v184, v184
	v_exp_f32_e32 v188, v188
	v_exp_f32_e32 v185, v185
	v_exp_f32_e32 v189, v189
	v_pk_add_f32 v[182:183], v[160:161], v[182:183] op_sel_hi:[0,1]
	v_pk_add_f32 v[186:187], v[160:161], v[186:187] op_sel_hi:[0,1]
	v_pk_add_f32 v[184:185], v[160:161], v[184:185] op_sel_hi:[0,1]
	v_pk_add_f32 v[188:189], v[160:161], v[188:189] op_sel_hi:[0,1]
	v_rcp_f32_e32 v182, v182
	v_rcp_f32_e32 v186, v186
	v_rcp_f32_e32 v183, v183
	v_rcp_f32_e32 v187, v187
	v_rcp_f32_e32 v184, v184
	v_rcp_f32_e32 v188, v188
	v_rcp_f32_e32 v185, v185
	v_rcp_f32_e32 v189, v189
	v_pk_mul_f32 v[56:57], v[56:57], v[182:183]
	v_pk_mul_f32 v[48:49], v[48:49], v[186:187]
	v_pk_mul_f32 v[58:59], v[58:59], v[184:185]
	v_pk_mul_f32 v[50:51], v[50:51], v[188:189]
	v_pk_mul_f32 v[56:57], v[60:61], v[56:57]
	v_pk_mul_f32 v[48:49], v[52:53], v[48:49]
; __device__ __forceinline__ float silu_f(float x) { return x * __builtin_amdgcn_rcpf(1.f + __builtin_amdgcn_exp2f(-1.4426950408889634f * x)); }
; #define BAR __builtin_amdgcn_s_barrier()
; template <int EPI>
; __device__ __forceinline__ void gemm_epi(const GemmArgs& G, const f32x4 (&a)[4][2], int rbase, int cbase, int fq, const float (&ssv)[4]) {
;     ...
;   for (int m = 0; m < 4; ++m) {
;     const int row = rbase + m * 16;
;     float rs = 1.f;
;     if constexpr (EPI == EPI_GU || EPI == EPI_EVIN || EPI == EPI_ODIN) rs = rsqrtf(ssv[m] * (1.f / 2048.f) + 1e-6f);
;     if constexpr (EPI == EPI_GU) {
;       const f32x4 gv = a[m][0] * rs, uv = a[m][1] * rs;
;       const int hc = (cbase >> 1) + fq * 4;
;       u32x2 o = {cvtpk(silu_f(gv[0]) * uv[0], silu_f(gv[1]) * uv[1]), cvtpk(silu_f(gv[2]) * uv[2], silu_f(gv[3]) * uv[3])};
;       *reinterpret_cast<u32x2*>(G.d0 + (size_t)(row - G.row0) * DFF + hc) = o;
;     ...
;   if (wr == 0) BAR;
	v_pk_mul_f32 v[58:59], v[62:63], v[58:59]
	v_pk_mul_f32 v[50:51], v[54:55], v[50:51]
	v_cvt_pk_bf16_f32 v200, v56, v57
	v_cvt_pk_bf16_f32 v202, v48, v49
	v_cvt_pk_bf16_f32 v201, v58, v59
	v_cvt_pk_bf16_f32 v203, v50, v51
	v_add_u32_e32 v210, 0x160000, v141
	v_add_u32_e32 v211, 0x18c000, v141
	global_store_dwordx2 v210, v[200:201], s[10:11]
	global_store_dwordx2 v211, v[202:203], s[10:11]
	v_pk_mul_f32 v[40:41], v[174:175], v[40:41] op_sel_hi:[0,1]
	v_pk_mul_f32 v[32:33], v[176:177], v[32:33] op_sel_hi:[0,1]
	v_pk_mul_f32 v[42:43], v[174:175], v[42:43] op_sel_hi:[0,1]
	v_pk_mul_f32 v[34:35], v[176:177], v[34:35] op_sel_hi:[0,1]
	v_pk_mul_f32 v[44:45], v[174:175], v[44:45] op_sel_hi:[0,1]
	v_pk_mul_f32 v[36:37], v[176:177], v[36:37] op_sel_hi:[0,1]
	v_pk_mul_f32 v[46:47], v[174:175], v[46:47] op_sel_hi:[0,1]
	v_pk_mul_f32 v[38:39], v[176:177], v[38:39] op_sel_hi:[0,1]
	v_pk_mul_f32 v[190:191], v[158:159], v[40:41] op_sel_hi:[0,1]
	v_pk_mul_f32 v[194:195], v[158:159], v[32:33] op_sel_hi:[0,1]
	v_pk_mul_f32 v[192:193], v[158:159], v[42:43] op_sel_hi:[0,1]
	v_pk_mul_f32 v[196:197], v[158:159], v[34:35] op_sel_hi:[0,1]
	v_exp_f32_e32 v190, v190
	v_exp_f32_e32 v194, v194
	v_exp_f32_e32 v191, v191
	v_exp_f32_e32 v195, v195
	v_exp_f32_e32 v192, v192
	v_exp_f32_e32 v196, v196
	v_exp_f32_e32 v193, v193
	v_exp_f32_e32 v197, v197
	v_pk_add_f32 v[190:191], v[160:161], v[190:191] op_sel_hi:[0,1]
	v_pk_add_f32 v[194:195], v[160:161], v[194:195] op_sel_hi:[0,1]
	v_pk_add_f32 v[192:193], v[160:161], v[192:193] op_sel_hi:[0,1]
	v_pk_add_f32 v[196:197], v[160:161], v[196:197] op_sel_hi:[0,1]
	v_rcp_f32_e32 v190, v190
	v_rcp_f32_e32 v194, v194
	v_rcp_f32_e32 v191, v191
	v_rcp_f32_e32 v195, v195
	v_rcp_f32_e32 v192, v192
	v_rcp_f32_e32 v196, v196
	v_rcp_f32_e32 v193, v193
	v_rcp_f32_e32 v197, v197
	v_pk_mul_f32 v[40:41], v[40:41], v[190:191]
	v_pk_mul_f32 v[32:33], v[32:33], v[194:195]
	v_pk_mul_f32 v[42:43], v[42:43], v[192:193]
	v_pk_mul_f32 v[34:35], v[34:35], v[196:197]
	v_pk_mul_f32 v[40:41], v[44:45], v[40:41]
	v_pk_mul_f32 v[32:33], v[36:37], v[32:33]
	v_pk_mul_f32 v[42:43], v[46:47], v[42:43]
	v_pk_mul_f32 v[34:35], v[38:39], v[34:35]
	v_cvt_pk_bf16_f32 v204, v40, v41
	v_cvt_pk_bf16_f32 v206, v32, v33
	v_cvt_pk_bf16_f32 v205, v42, v43
	v_cvt_pk_bf16_f32 v207, v34, v35
	v_add_u32_e32 v212, 0x1b8000, v141
	v_add_u32_e32 v213, 0x1e4000, v141
	global_store_dwordx2 v212, v[204:205], s[10:11]
	global_store_dwordx2 v213, v[206:207], s[10:11]
	v_pk_mul_f32 v[24:25], v[170:171], v[24:25] op_sel_hi:[0,1]
	v_pk_mul_f32 v[16:17], v[172:173], v[16:17] op_sel_hi:[0,1]
	v_pk_mul_f32 v[26:27], v[170:171], v[26:27] op_sel_hi:[0,1]
	v_pk_mul_f32 v[18:19], v[172:173], v[18:19] op_sel_hi:[0,1]
	v_pk_mul_f32 v[28:29], v[170:171], v[28:29] op_sel_hi:[0,1]
	v_pk_mul_f32 v[20:21], v[172:173], v[20:21] op_sel_hi:[0,1]
	v_pk_mul_f32 v[30:31], v[170:171], v[30:31] op_sel_hi:[0,1]
	v_pk_mul_f32 v[22:23], v[172:173], v[22:23] op_sel_hi:[0,1]
	v_pk_mul_f32 v[182:183], v[158:159], v[24:25] op_sel_hi:[0,1]
	v_pk_mul_f32 v[186:187], v[158:159], v[16:17] op_sel_hi:[0,1]
	v_pk_mul_f32 v[184:185], v[158:159], v[26:27] op_sel_hi:[0,1]
	v_pk_mul_f32 v[188:189], v[158:159], v[18:19] op_sel_hi:[0,1]
	v_exp_f32_e32 v182, v182
	v_exp_f32_e32 v186, v186
	v_exp_f32_e32 v183, v183
	v_exp_f32_e32 v187, v187
	v_exp_f32_e32 v184, v184
	v_exp_f32_e32 v188, v188
	v_exp_f32_e32 v185, v185
	v_exp_f32_e32 v189, v189
	v_pk_add_f32 v[182:183], v[160:161], v[182:183] op_sel_hi:[0,1]
	v_pk_add_f32 v[186:187], v[160:161], v[186:187] op_sel_hi:[0,1]
	v_pk_add_f32 v[184:185], v[160:161], v[184:185] op_sel_hi:[0,1]
	v_pk_add_f32 v[188:189], v[160:161], v[188:189] op_sel_hi:[0,1]
	v_rcp_f32_e32 v182, v182
	v_rcp_f32_e32 v186, v186
	v_rcp_f32_e32 v183, v183
	v_rcp_f32_e32 v187, v187
	v_rcp_f32_e32 v184, v184
	v_rcp_f32_e32 v188, v188
	v_rcp_f32_e32 v185, v185
	v_rcp_f32_e32 v189, v189
	v_pk_mul_f32 v[24:25], v[24:25], v[182:183]
	v_pk_mul_f32 v[16:17], v[16:17], v[186:187]
	v_pk_mul_f32 v[26:27], v[26:27], v[184:185]
	v_pk_mul_f32 v[18:19], v[18:19], v[188:189]
	v_pk_mul_f32 v[24:25], v[28:29], v[24:25]
	v_pk_mul_f32 v[16:17], v[20:21], v[16:17]
	v_pk_mul_f32 v[26:27], v[30:31], v[26:27]
	v_pk_mul_f32 v[18:19], v[22:23], v[18:19]
	v_cvt_pk_bf16_f32 v200, v24, v25
	v_cvt_pk_bf16_f32 v202, v16, v17
	v_cvt_pk_bf16_f32 v201, v26, v27
	v_cvt_pk_bf16_f32 v203, v18, v19
	v_add_u32_e32 v210, 0x160080, v141
	v_add_u32_e32 v211, 0x18c080, v141
	global_store_dwordx2 v210, v[200:201], s[10:11]
	global_store_dwordx2 v211, v[202:203], s[10:11]
	v_pk_mul_f32 v[8:9], v[174:175], v[8:9] op_sel_hi:[0,1]
	v_pk_mul_f32 v[0:1], v[176:177], v[0:1] op_sel_hi:[0,1]
	v_pk_mul_f32 v[10:11], v[174:175], v[10:11] op_sel_hi:[0,1]
	v_pk_mul_f32 v[2:3], v[176:177], v[2:3] op_sel_hi:[0,1]
	v_pk_mul_f32 v[12:13], v[174:175], v[12:13] op_sel_hi:[0,1]
	v_pk_mul_f32 v[4:5], v[176:177], v[4:5] op_sel_hi:[0,1]
	v_pk_mul_f32 v[14:15], v[174:175], v[14:15] op_sel_hi:[0,1]
	v_pk_mul_f32 v[6:7], v[176:177], v[6:7] op_sel_hi:[0,1]
	v_pk_mul_f32 v[190:191], v[158:159], v[8:9] op_sel_hi:[0,1]
	v_pk_mul_f32 v[194:195], v[158:159], v[0:1] op_sel_hi:[0,1]
	v_pk_mul_f32 v[192:193], v[158:159], v[10:11] op_sel_hi:[0,1]
	v_pk_mul_f32 v[196:197], v[158:159], v[2:3] op_sel_hi:[0,1]
	v_exp_f32_e32 v190, v190
	v_exp_f32_e32 v194, v194
	v_exp_f32_e32 v191, v191
	v_exp_f32_e32 v195, v195
	v_exp_f32_e32 v192, v192
	v_exp_f32_e32 v196, v196
	v_exp_f32_e32 v193, v193
	v_exp_f32_e32 v197, v197
	v_pk_add_f32 v[190:191], v[160:161], v[190:191] op_sel_hi:[0,1]
	v_pk_add_f32 v[194:195], v[160:161], v[194:195] op_sel_hi:[0,1]
	v_pk_add_f32 v[192:193], v[160:161], v[192:193] op_sel_hi:[0,1]
	v_pk_add_f32 v[196:197], v[160:161], v[196:197] op_sel_hi:[0,1]
	v_rcp_f32_e32 v190, v190
	v_rcp_f32_e32 v194, v194
	v_rcp_f32_e32 v191, v191
	v_rcp_f32_e32 v195, v195
	v_rcp_f32_e32 v192, v192
	v_rcp_f32_e32 v196, v196
	v_rcp_f32_e32 v193, v193
	v_rcp_f32_e32 v197, v197
	v_pk_mul_f32 v[8:9], v[8:9], v[190:191]
	v_pk_mul_f32 v[0:1], v[0:1], v[194:195]
	v_pk_mul_f32 v[10:11], v[10:11], v[192:193]
	v_pk_mul_f32 v[2:3], v[2:3], v[196:197]
	v_pk_mul_f32 v[8:9], v[12:13], v[8:9]
	v_pk_mul_f32 v[0:1], v[4:5], v[0:1]
	v_pk_mul_f32 v[10:11], v[14:15], v[10:11]
	v_pk_mul_f32 v[2:3], v[6:7], v[2:3]
	v_cvt_pk_bf16_f32 v204, v8, v9
	v_cvt_pk_bf16_f32 v206, v0, v1
	v_cvt_pk_bf16_f32 v205, v10, v11
	v_cvt_pk_bf16_f32 v207, v2, v3
	v_add_u32_e32 v212, 0x1b8080, v141
	v_add_u32_e32 v213, 0x1e4080, v141
	global_store_dwordx2 v212, v[204:205], s[10:11]
	global_store_dwordx2 v213, v[206:207], s[10:11]
	v_readfirstlane_b32 s16, v224
	s_nop 3
	s_bitcmp0_b32 s16, 8
	s_cbranch_scc0 .Lmy_gu_nobar
	s_barrier
.Lmy_gu_nobar:
	s_andn2_b64 vcc, exec, s[14:15]
	s_mov_b32 s18, s25
	s_cbranch_vccz .LBB0_2571

; #define STAGE_A(P, br, kt) do { const char* _base = (const char*)(((kt) < G.ksplit ? G.A1 : A2m) + (long)(br) * G.lda + (long)(kt) * BK); \
;     __builtin_amdgcn_global_load_lds((const unsigned*)(_base + aoff0), (unsigned*)((char*)(P) + sb0), 16, 0, 0); \
;     __builtin_amdgcn_global_load_lds((const unsigned*)(_base + aoff1), (unsigned*)((char*)(P) + sb1), 16, 0, 0); } while (0)
; #define LDA(dst, b, h) for (int m = 0; m < 4; ++m) for (int k = 0; k < 2; ++k) \
;     dst[m][k] = *reinterpret_cast<const bf16x8*>(a_rd + ((b) * 2 + (h)) * (HT * 2) + m * 2048 + k * 1024)
; #define LDB(dst, b, h) for (int n = 0; n < 2; ++n) for (int k = 0; k < 2; ++k) \
;     dst[n][k] = *reinterpret_cast<const bf16x8*>(b_rd + ((b) * 2 + (h)) * (HT * 2) + n * 2048 + k * 1024)
; #define MMA(ai, bj, At_, Bt_) do { __builtin_amdgcn_s_setprio(1); \
;     for (int m = 0; m < 4; ++m) for (int n = 0; n < 2; ++n) for (int k = 0; k < 2; ++k) \
;       acc[ai][bj][m][n] = __builtin_amdgcn_mfma_f32_16x16x32_bf16(Bt_[n][k], At_[m][k], acc[ai][bj][m][n], 0, 0, 0); \
;     __builtin_amdgcn_s_setprio(0); } while (0)
; #define WAIT_V(n) asm volatile("s_waitcnt vmcnt(" #n ")" ::: "memory")
; #define WAIT_L(n) asm volatile("s_waitcnt lgkmcnt(" #n ")" ::: "memory")
; #define BAR __builtin_amdgcn_s_barrier()
;     ...
;   float ssv[2][4] = {};
;   if constexpr (EPI == EPI_GU || EPI == EPI_EVIN || EPI == EPI_ODIN) {
; #pragma unroll
;     for (int ai = 0; ai < 2; ++ai)
; #pragma unroll
;       for (int m = 0; m < 4; ++m) ssv[ai][m] = G.ssr[brow + ai * HALF + wr * 64 + m * 16 + fr];
;   }
;   { LDB(B0, 0, 0); LDA(At, 0, 0); STAGE_A(SA(1, 1), brow + HALF, nt - 1);
;     BAR; WAIT_L(0); MMA(0, 0, At, B0); BAR;
;     LDB(B1, 0, 1); BAR; WAIT_L(0); MMA(0, 1, At, B1); BAR;
;     LDA(At, 0, 1); WAIT_V(4); BAR; WAIT_L(0); MMA(1, 0, At, B0); MMA(1, 1, At, B1); BAR; }
.Lmy_kexit_4:
	s_waitcnt vmcnt(6)
	v_not_b32_e32 v250, 63
	v_mov_b32_e32 v251, 0x41b17218
	v_or_b32_e32 v130, s28, v152
	v_lshl_add_u32 v130, v151, 6, v130
	v_add_u32_e32 v134, 0x80, v130
	v_ashrrev_i32_e32 v135, 31, v134
	v_lshl_add_u64 v[140:141], v[134:135], 2, s[12:13]
	v_add_u32_e32 v134, 0x90, v130
	v_ashrrev_i32_e32 v131, 31, v130
	v_ashrrev_i32_e32 v135, 31, v134
	v_lshl_add_u64 v[132:133], v[130:131], 2, s[12:13]
	v_lshl_add_u64 v[152:153], v[134:135], 2, s[12:13]
	v_add_u32_e32 v134, 0xa0, v130
	v_add_u32_e32 v130, 0xb0, v130
	s_or_b32 s21, s28, 0x80
	v_ashrrev_i32_e32 v135, 31, v134
	v_ashrrev_i32_e32 v131, 31, v130
	s_mul_i32 s18, s21, 0x1080
	v_lshl_add_u64 v[154:155], v[134:135], 2, s[12:13]
	v_lshl_add_u64 v[156:157], v[130:131], 2, s[12:13]
	global_load_dword v139, v[132:133], off
	global_load_dword v138, v[132:133], off offset:64
	global_load_dword v137, v[132:133], off offset:128
	global_load_dword v134, v[132:133], off offset:192
	s_nop 0
	global_load_dword v133, v[140:141], off
	global_load_dword v132, v[152:153], off
	global_load_dword v131, v[154:155], off
	global_load_dword v130, v[156:157], off
	s_mul_hi_i32 s19, s21, 0x1080
	s_add_u32 s18, s23, s18
	s_addc_u32 s19, s24, s19
	v_lshl_add_u64 v[140:141], s[18:19], 0, v[180:181]
	v_readfirstlane_b32 s31, v162
	v_lshl_add_u64 v[140:141], v[140:141], 0, s[46:47]
	s_mov_b32 m0, s31
	ds_read_b128 v[152:155], v150
	ds_read_b128 v[164:167], v150 offset:1024
	ds_read_b128 v[168:171], v150 offset:2048
	ds_read_b128 v[172:175], v150 offset:3072
	ds_read_b128 v[176:179], v149
	ds_read_b128 v[182:185], v149 offset:1024
	ds_read_b128 v[186:189], v149 offset:2048
	ds_read_b128 v[190:193], v149 offset:3072
	ds_read_b128 v[194:197], v149 offset:4096
	ds_read_b128 v[198:201], v149 offset:5120
	ds_read_b128 v[202:205], v149 offset:6144
	ds_read_b128 v[206:209], v149 offset:7168
	global_load_lds_dwordx4 v[140:141], off
	v_lshl_add_u64 v[140:141], s[18:19], 0, v[128:129]
	v_readfirstlane_b32 s18, v163
	v_lshl_add_u64 v[140:141], v[140:141], 0, s[46:47]
	s_mov_b32 m0, s18
	s_nop 0
	global_load_lds_dwordx4 v[140:141], off
	s_barrier
	s_waitcnt lgkmcnt(0)
	s_setprio 1
	s_waitcnt lgkmcnt(0)
	v_mfma_f32_16x16x32_bf16 v[124:127], v[152:155], v[176:179], v[124:127]
	v_mfma_f32_16x16x32_bf16 v[116:119], v[152:155], v[186:189], v[116:119]
	v_mfma_f32_16x16x32_bf16 v[108:111], v[152:155], v[194:197], v[108:111]
	v_mfma_f32_16x16x32_bf16 v[100:103], v[152:155], v[202:205], v[100:103]
	v_mfma_f32_16x16x32_bf16 v[124:127], v[164:167], v[182:185], v[124:127]
	v_mfma_f32_16x16x32_bf16 v[120:123], v[168:171], v[176:179], v[120:123]
	v_mfma_f32_16x16x32_bf16 v[116:119], v[164:167], v[190:193], v[116:119]
	v_mfma_f32_16x16x32_bf16 v[112:115], v[168:171], v[186:189], v[112:115]
	v_mfma_f32_16x16x32_bf16 v[108:111], v[164:167], v[198:201], v[108:111]
	v_mfma_f32_16x16x32_bf16 v[104:107], v[168:171], v[194:197], v[104:107]
	v_mfma_f32_16x16x32_bf16 v[100:103], v[164:167], v[206:209], v[100:103]
	v_mfma_f32_16x16x32_bf16 v[96:99], v[168:171], v[202:205], v[96:99]
	v_mfma_f32_16x16x32_bf16 v[210:213], v[172:175], v[182:185], v[120:123]
	v_mfma_f32_16x16x32_bf16 v[214:217], v[172:175], v[190:193], v[112:115]
	s_setprio 2
	s_barrier
	v_mfma_f32_16x16x32_bf16 v[218:221], v[172:175], v[198:201], v[104:107]
	v_mfma_f32_16x16x32_bf16 v[230:233], v[172:175], v[206:209], v[96:99]
	s_setprio 0
	s_nop 1
	ds_read_b128 v[96:99], v150 offset:16384
	ds_read_b128 v[104:107], v150 offset:17408
	ds_read_b128 v[112:115], v150 offset:18432
	ds_read_b128 v[120:123], v150 offset:19456
	s_barrier
	s_waitcnt lgkmcnt(0)
	s_setprio 1
	s_waitcnt lgkmcnt(0)
	v_mfma_f32_16x16x32_bf16 v[92:95], v[96:99], v[176:179], v[92:95]
	v_mfma_f32_16x16x32_bf16 v[84:87], v[96:99], v[186:189], v[84:87]
	v_mfma_f32_16x16x32_bf16 v[76:79], v[96:99], v[194:197], v[76:79]
	v_mfma_f32_16x16x32_bf16 v[68:71], v[96:99], v[202:205], v[68:71]
	v_mfma_f32_16x16x32_bf16 v[92:95], v[104:107], v[182:185], v[92:95]
	v_mfma_f32_16x16x32_bf16 v[88:91], v[112:115], v[176:179], v[88:91]
	v_mfma_f32_16x16x32_bf16 v[84:87], v[104:107], v[190:193], v[84:87]
	v_mfma_f32_16x16x32_bf16 v[80:83], v[112:115], v[186:189], v[80:83]
	v_mfma_f32_16x16x32_bf16 v[76:79], v[104:107], v[198:201], v[76:79]
	v_mfma_f32_16x16x32_bf16 v[72:75], v[112:115], v[194:197], v[72:75]
	v_mfma_f32_16x16x32_bf16 v[68:71], v[104:107], v[206:209], v[68:71]
	v_mfma_f32_16x16x32_bf16 v[64:67], v[112:115], v[202:205], v[64:67]
	v_mfma_f32_16x16x32_bf16 v[176:179], v[120:123], v[182:185], v[88:91]
	v_mfma_f32_16x16x32_bf16 v[182:185], v[120:123], v[190:193], v[80:83]
	s_setprio 2
	s_barrier
	v_mfma_f32_16x16x32_bf16 v[186:189], v[120:123], v[198:201], v[72:75]
	v_mfma_f32_16x16x32_bf16 v[190:193], v[120:123], v[206:209], v[64:67]
	s_setprio 0
	s_nop 1
	ds_read_b128 v[64:67], v149 offset:16384
	ds_read_b128 v[72:75], v149 offset:17408
	ds_read_b128 v[80:83], v149 offset:18432
	ds_read_b128 v[88:91], v149 offset:19456
	ds_read_b128 v[194:197], v149 offset:20480
	ds_read_b128 v[198:201], v149 offset:21504
	ds_read_b128 v[202:205], v149 offset:22528
	ds_read_b128 v[206:209], v149 offset:23552
	s_waitcnt vmcnt(4)
	s_barrier
; #define STAGE_A(P, br, kt) do { const char* _base = (const char*)(((kt) < G.ksplit ? G.A1 : A2m) + (long)(br) * G.lda + (long)(kt) * BK); \
;     __builtin_amdgcn_global_load_lds((const unsigned*)(_base + aoff0), (unsigned*)((char*)(P) + sb0), 16, 0, 0); \
;     __builtin_amdgcn_global_load_lds((const unsigned*)(_base + aoff1), (unsigned*)((char*)(P) + sb1), 16, 0, 0); } while (0)
; #define LDA(dst, b, h) for (int m = 0; m < 4; ++m) for (int k = 0; k < 2; ++k) \
;     dst[m][k] = *reinterpret_cast<const bf16x8*>(a_rd + ((b) * 2 + (h)) * (HT * 2) + m * 2048 + k * 1024)
; #define LDB(dst, b, h) for (int n = 0; n < 2; ++n) for (int k = 0; k < 2; ++k) \
;     dst[n][k] = *reinterpret_cast<const bf16x8*>(b_rd + ((b) * 2 + (h)) * (HT * 2) + n * 2048 + k * 1024)
; #define MMA(ai, bj, At_, Bt_) do { __builtin_amdgcn_s_setprio(1); \
;     for (int m = 0; m < 4; ++m) for (int n = 0; n < 2; ++n) for (int k = 0; k < 2; ++k) \
;       acc[ai][bj][m][n] = __builtin_amdgcn_mfma_f32_16x16x32_bf16(Bt_[n][k], At_[m][k], acc[ai][bj][m][n], 0, 0, 0); \
;     __builtin_amdgcn_s_setprio(0); } while (0)
; #define WAIT_V(n) asm volatile("s_waitcnt vmcnt(" #n ")" ::: "memory")
; #define WAIT_L(n) asm volatile("s_waitcnt lgkmcnt(" #n ")" ::: "memory")
; #define BAR __builtin_amdgcn_s_barrier()
;     ...
;   { LDB(B0, 0, 0); LDA(At, 0, 0); STAGE_A(SA(1, 1), brow + HALF, nt - 1);
;     BAR; WAIT_L(0); MMA(0, 0, At, B0); BAR;
;     LDB(B1, 0, 1); BAR; WAIT_L(0); MMA(0, 1, At, B1); BAR;
;     LDA(At, 0, 1); WAIT_V(4); BAR; WAIT_L(0); MMA(1, 0, At, B0); MMA(1, 1, At, B1); BAR; }
;   { LDB(B0, 1, 0); LDA(At, 1, 0); WAIT_V(2); BAR; WAIT_L(0); MMA(0, 0, At, B0); BAR;
;     LDB(B1, 1, 1); WAIT_V(0); BAR; WAIT_L(0); MMA(0, 1, At, B1); BAR;
	s_waitcnt lgkmcnt(0)
	s_setprio 1
	s_waitcnt lgkmcnt(0)
	v_mfma_f32_16x16x32_bf16 v[60:63], v[152:155], v[64:67], v[60:63]
	v_mfma_f32_16x16x32_bf16 v[52:55], v[152:155], v[80:83], v[52:55]
	v_mfma_f32_16x16x32_bf16 v[44:47], v[152:155], v[194:197], v[44:47]
	v_mfma_f32_16x16x32_bf16 v[36:39], v[152:155], v[202:205], v[36:39]
	v_mfma_f32_16x16x32_bf16 v[60:63], v[164:167], v[72:75], v[60:63]
	v_mfma_f32_16x16x32_bf16 v[56:59], v[168:171], v[64:67], v[56:59]
	v_mfma_f32_16x16x32_bf16 v[52:55], v[164:167], v[88:91], v[52:55]
	v_mfma_f32_16x16x32_bf16 v[48:51], v[168:171], v[80:83], v[48:51]
	v_mfma_f32_16x16x32_bf16 v[44:47], v[164:167], v[198:201], v[44:47]
	v_mfma_f32_16x16x32_bf16 v[40:43], v[168:171], v[194:197], v[40:43]
	v_mfma_f32_16x16x32_bf16 v[36:39], v[164:167], v[206:209], v[36:39]
	v_mfma_f32_16x16x32_bf16 v[32:35], v[168:171], v[202:205], v[32:35]
	v_mfma_f32_16x16x32_bf16 v[238:241], v[172:175], v[72:75], v[56:59]
	v_mfma_f32_16x16x32_bf16 v[246:249], v[172:175], v[88:91], v[48:51]
	v_mfma_f32_16x16x32_bf16 v[234:237], v[172:175], v[198:201], v[40:43]
	v_mfma_f32_16x16x32_bf16 v[152:155], v[172:175], v[206:209], v[32:35]
	s_setprio 0
	s_setprio 1
	v_mfma_f32_16x16x32_bf16 v[28:31], v[96:99], v[64:67], v[28:31]
	v_mfma_f32_16x16x32_bf16 v[20:23], v[96:99], v[80:83], v[20:23]
	v_mfma_f32_16x16x32_bf16 v[12:15], v[96:99], v[194:197], v[12:15]
	v_mfma_f32_16x16x32_bf16 v[4:7], v[96:99], v[202:205], v[4:7]
	v_mfma_f32_16x16x32_bf16 v[28:31], v[104:107], v[72:75], v[28:31]
	v_mfma_f32_16x16x32_bf16 v[24:27], v[112:115], v[64:67], v[24:27]
	v_mfma_f32_16x16x32_bf16 v[20:23], v[104:107], v[88:91], v[20:23]
	v_mfma_f32_16x16x32_bf16 v[16:19], v[112:115], v[80:83], v[16:19]
	v_mfma_f32_16x16x32_bf16 v[12:15], v[104:107], v[198:201], v[12:15]
	v_mfma_f32_16x16x32_bf16 v[8:11], v[112:115], v[194:197], v[8:11]
	v_mfma_f32_16x16x32_bf16 v[4:7], v[104:107], v[206:209], v[4:7]
	v_mfma_f32_16x16x32_bf16 v[0:3], v[112:115], v[202:205], v[0:3]
	v_mfma_f32_16x16x32_bf16 v[162:165], v[120:123], v[72:75], v[24:27]
	v_mfma_f32_16x16x32_bf16 v[166:169], v[120:123], v[88:91], v[16:19]
	s_setprio 2
	s_barrier
	v_mfma_f32_16x16x32_bf16 v[170:173], v[120:123], v[198:201], v[8:11]
	v_mfma_f32_16x16x32_bf16 v[194:197], v[120:123], v[206:209], v[0:3]
	s_setprio 0
	s_nop 1
	ds_read_b128 v[0:3], v150 offset:32768
	ds_read_b128 v[8:11], v150 offset:33792
	ds_read_b128 v[16:19], v150 offset:34816
	ds_read_b128 v[24:27], v150 offset:35840
	ds_read_b128 v[32:35], v149 offset:32768
	ds_read_b128 v[40:43], v149 offset:33792
	ds_read_b128 v[48:51], v149 offset:34816
	ds_read_b128 v[56:59], v149 offset:35840
	ds_read_b128 v[64:67], v149 offset:36864
	ds_read_b128 v[198:201], v149 offset:37888
	ds_read_b128 v[202:205], v149 offset:38912
	ds_read_b128 v[206:209], v149 offset:39936
	s_waitcnt vmcnt(2)
	s_barrier
	s_waitcnt lgkmcnt(0)
	s_setprio 1
	s_waitcnt lgkmcnt(0)
	v_mfma_f32_16x16x32_bf16 v[72:75], v[0:3], v[32:35], v[124:127]
	v_mfma_f32_16x16x32_bf16 v[120:123], v[8:11], v[40:43], v[72:75]
	v_mfma_f32_16x16x32_bf16 v[72:75], v[16:19], v[32:35], v[210:213]
	v_mfma_f32_16x16x32_bf16 v[124:127], v[24:27], v[40:43], v[72:75]
	v_mfma_f32_16x16x32_bf16 v[72:75], v[0:3], v[48:51], v[116:119]
	v_mfma_f32_16x16x32_bf16 v[112:115], v[8:11], v[56:59], v[72:75]
	v_mfma_f32_16x16x32_bf16 v[72:75], v[16:19], v[48:51], v[214:217]
	v_mfma_f32_16x16x32_bf16 v[116:119], v[24:27], v[56:59], v[72:75]
	v_mfma_f32_16x16x32_bf16 v[72:75], v[0:3], v[64:67], v[108:111]
	v_mfma_f32_16x16x32_bf16 v[104:107], v[8:11], v[198:201], v[72:75]
	v_mfma_f32_16x16x32_bf16 v[72:75], v[16:19], v[64:67], v[218:221]
	v_mfma_f32_16x16x32_bf16 v[108:111], v[24:27], v[198:201], v[72:75]
	v_mfma_f32_16x16x32_bf16 v[72:75], v[0:3], v[202:205], v[100:103]
	v_mfma_f32_16x16x32_bf16 v[96:99], v[8:11], v[206:209], v[72:75]
	s_setprio 2
	s_barrier
	v_mfma_f32_16x16x32_bf16 v[72:75], v[16:19], v[202:205], v[230:233]
	v_mfma_f32_16x16x32_bf16 v[100:103], v[24:27], v[206:209], v[72:75]
	s_setprio 0
	ds_read_b128 v[210:213], v150 offset:49152
	ds_read_b128 v[214:217], v150 offset:50176
	ds_read_b128 v[218:221], v150 offset:51200
	ds_read_b128 v[230:233], v150 offset:52224
	s_waitcnt vmcnt(0)
	s_barrier
	s_waitcnt lgkmcnt(0)
	s_setprio 1
	s_waitcnt lgkmcnt(0)
	v_mfma_f32_16x16x32_bf16 v[72:75], v[210:213], v[32:35], v[92:95]
	v_mfma_f32_16x16x32_bf16 v[32:35], v[218:221], v[32:35], v[176:179]
	v_mfma_f32_16x16x32_bf16 v[92:95], v[230:233], v[40:43], v[32:35]
	v_mfma_f32_16x16x32_bf16 v[32:35], v[210:213], v[48:51], v[84:87]
	v_mfma_f32_16x16x32_bf16 v[80:83], v[214:217], v[56:59], v[32:35]
	v_mfma_f32_16x16x32_bf16 v[32:35], v[218:221], v[48:51], v[182:185]
	v_mfma_f32_16x16x32_bf16 v[84:87], v[230:233], v[56:59], v[32:35]
	v_mfma_f32_16x16x32_bf16 v[32:35], v[210:213], v[64:67], v[76:79]
	v_mfma_f32_16x16x32_bf16 v[88:91], v[214:217], v[40:43], v[72:75]
	v_mfma_f32_16x16x32_bf16 v[72:75], v[214:217], v[198:201], v[32:35]
	v_mfma_f32_16x16x32_bf16 v[32:35], v[218:221], v[64:67], v[186:189]
	v_mfma_f32_16x16x32_bf16 v[76:79], v[230:233], v[198:201], v[32:35]
	v_mfma_f32_16x16x32_bf16 v[32:35], v[210:213], v[202:205], v[68:71]
	v_mfma_f32_16x16x32_bf16 v[64:67], v[214:217], v[206:209], v[32:35]
	s_setprio 2
	s_barrier
; #define STAGE_A(P, br, kt) do { const char* _base = (const char*)(((kt) < G.ksplit ? G.A1 : A2m) + (long)(br) * G.lda + (long)(kt) * BK); \
;     __builtin_amdgcn_global_load_lds((const unsigned*)(_base + aoff0), (unsigned*)((char*)(P) + sb0), 16, 0, 0); \
;     __builtin_amdgcn_global_load_lds((const unsigned*)(_base + aoff1), (unsigned*)((char*)(P) + sb1), 16, 0, 0); } while (0)
; #define STAGE_B(P, br, kt) do { const char* _base = (const char*)(G.Bt + (long)(br) * G.ldb + (long)(kt) * BK); \
;     __builtin_amdgcn_global_load_lds((const unsigned*)(_base + boff0), (unsigned*)((char*)(P) + sb0), 16, 0, 0); \
;     __builtin_amdgcn_global_load_lds((const unsigned*)(_base + boff1), (unsigned*)((char*)(P) + sb1), 16, 0, 0); } while (0)
; #define LDA(dst, b, h) for (int m = 0; m < 4; ++m) for (int k = 0; k < 2; ++k) \
;     dst[m][k] = *reinterpret_cast<const bf16x8*>(a_rd + ((b) * 2 + (h)) * (HT * 2) + m * 2048 + k * 1024)
; #define LDB(dst, b, h) for (int n = 0; n < 2; ++n) for (int k = 0; k < 2; ++k) \
;     dst[n][k] = *reinterpret_cast<const bf16x8*>(b_rd + ((b) * 2 + (h)) * (HT * 2) + n * 2048 + k * 1024)
; #define MMA(ai, bj, At_, Bt_) do { __builtin_amdgcn_s_setprio(1); \
;     for (int m = 0; m < 4; ++m) for (int n = 0; n < 2; ++n) for (int k = 0; k < 2; ++k) \
;       acc[ai][bj][m][n] = __builtin_amdgcn_mfma_f32_16x16x32_bf16(Bt_[n][k], At_[m][k], acc[ai][bj][m][n], 0, 0, 0); \
;     __builtin_amdgcn_s_setprio(0); } while (0)
; #define WAIT_V(n) asm volatile("s_waitcnt vmcnt(" #n ")" ::: "memory")
; #define WAIT_L(n) asm volatile("s_waitcnt lgkmcnt(" #n ")" ::: "memory")
; #define BAR __builtin_amdgcn_s_barrier()
;     ...
;     LDB(B1, 1, 1); WAIT_V(0); BAR; WAIT_L(0); MMA(0, 1, At, B1); BAR;
;     LDA(At, 1, 1); BAR; WAIT_L(0); MMA(1, 0, At, B0); MMA(1, 1, At, B1); BAR; }
;   if (wr == 0) BAR;
;   if (EPI != EPI_RESID && has_next) {
;     STAGE_B(SB(0, 0), nbcol, 0); STAGE_A(SA(0, 0), nbrow, 0);
;     STAGE_B(SB(0, 1), nbcol + HALF, 0); STAGE_A(SA(0, 1), nbrow + HALF, 0);
;   }
	v_mfma_f32_16x16x32_bf16 v[32:35], v[218:221], v[202:205], v[190:193]
	v_mfma_f32_16x16x32_bf16 v[68:71], v[230:233], v[206:209], v[32:35]
	s_setprio 0
	ds_read_b128 v[174:177], v149 offset:49152
	ds_read_b128 v[182:185], v149 offset:50176
	ds_read_b128 v[186:189], v149 offset:51200
	ds_read_b128 v[190:193], v149 offset:52224
	ds_read_b128 v[198:201], v149 offset:53248
	ds_read_b128 v[202:205], v149 offset:54272
	ds_read_b128 v[206:209], v149 offset:55296
	ds_read_b128 v[148:151], v149 offset:56320
	s_barrier
	s_waitcnt lgkmcnt(0)
	s_setprio 1
	s_waitcnt lgkmcnt(0)
	v_mfma_f32_16x16x32_bf16 v[32:35], v[0:3], v[174:177], v[60:63]
	v_mfma_f32_16x16x32_bf16 v[56:59], v[8:11], v[182:185], v[32:35]
	v_mfma_f32_16x16x32_bf16 v[32:35], v[16:19], v[174:177], v[238:241]
	v_mfma_f32_16x16x32_bf16 v[60:63], v[24:27], v[182:185], v[32:35]
	v_mfma_f32_16x16x32_bf16 v[32:35], v[0:3], v[186:189], v[52:55]
	v_mfma_f32_16x16x32_bf16 v[48:51], v[8:11], v[190:193], v[32:35]
	v_mfma_f32_16x16x32_bf16 v[32:35], v[16:19], v[186:189], v[246:249]
	v_mfma_f32_16x16x32_bf16 v[52:55], v[24:27], v[190:193], v[32:35]
	v_mfma_f32_16x16x32_bf16 v[32:35], v[0:3], v[198:201], v[44:47]
	v_mfma_f32_16x16x32_bf16 v[40:43], v[8:11], v[202:205], v[32:35]
	v_mfma_f32_16x16x32_bf16 v[32:35], v[16:19], v[198:201], v[234:237]
	v_mfma_f32_16x16x32_bf16 v[0:3], v[0:3], v[206:209], v[36:39]
	v_mfma_f32_16x16x32_bf16 v[44:47], v[24:27], v[202:205], v[32:35]
	v_mfma_f32_16x16x32_bf16 v[32:35], v[8:11], v[148:151], v[0:3]
	v_mfma_f32_16x16x32_bf16 v[0:3], v[16:19], v[206:209], v[152:155]
	v_mfma_f32_16x16x32_bf16 v[36:39], v[24:27], v[148:151], v[0:3]
	s_setprio 0
	s_setprio 1
	v_mfma_f32_16x16x32_bf16 v[0:3], v[210:213], v[174:177], v[28:31]
	v_mfma_f32_16x16x32_bf16 v[24:27], v[214:217], v[182:185], v[0:3]
	v_mfma_f32_16x16x32_bf16 v[0:3], v[218:221], v[174:177], v[162:165]
	v_mfma_f32_16x16x32_bf16 v[28:31], v[230:233], v[182:185], v[0:3]
	v_mfma_f32_16x16x32_bf16 v[0:3], v[210:213], v[186:189], v[20:23]
	v_mfma_f32_16x16x32_bf16 v[16:19], v[214:217], v[190:193], v[0:3]
	v_mfma_f32_16x16x32_bf16 v[0:3], v[218:221], v[186:189], v[166:169]
	v_mfma_f32_16x16x32_bf16 v[20:23], v[230:233], v[190:193], v[0:3]
	v_mfma_f32_16x16x32_bf16 v[0:3], v[210:213], v[198:201], v[12:15]
	v_mfma_f32_16x16x32_bf16 v[8:11], v[214:217], v[202:205], v[0:3]
	v_mfma_f32_16x16x32_bf16 v[0:3], v[218:221], v[198:201], v[170:173]
	v_mfma_f32_16x16x32_bf16 v[12:15], v[230:233], v[202:205], v[0:3]
	v_mfma_f32_16x16x32_bf16 v[0:3], v[210:213], v[206:209], v[4:7]
	v_mfma_f32_16x16x32_bf16 v[4:7], v[218:221], v[206:209], v[194:197]
	s_setprio 2
	s_barrier
	v_mfma_f32_16x16x32_bf16 v[0:3], v[214:217], v[148:151], v[0:3]
	v_mfma_f32_16x16x32_bf16 v[4:7], v[230:233], v[148:151], v[4:7]
	s_setprio 0
	s_andn2_b64 vcc, exec, s[16:17]
	v_mov_b32_e32 v249, v245
	s_cbranch_vccnz .LBB0_2558
	s_mul_i32 s16, s27, 0x840
	s_ashr_i32 s17, s16, 31
	s_lshl_b64 s[16:17], s[16:17], 1
	s_add_u32 s16, s8, s16
	s_addc_u32 s17, s9, s17
	v_readfirstlane_b32 s18, v159
	v_lshl_add_u64 v[140:141], s[16:17], 0, v[180:181]
	s_mov_b32 m0, s18
	s_mul_i32 s18, s26, 0x1080
	global_load_lds_dwordx4 v[140:141], off
	v_lshl_add_u64 v[140:141], s[16:17], 0, v[128:129]
	v_readfirstlane_b32 s16, v160
	s_mov_b32 m0, s16
	s_mul_hi_i32 s17, s26, 0x1080
	s_add_u32 s16, s23, s18
	s_addc_u32 s17, s24, s17
	v_readfirstlane_b32 s19, v147
	global_load_lds_dwordx4 v[140:141], off
	v_lshl_add_u64 v[140:141], s[16:17], 0, v[180:181]
	s_mov_b32 m0, s19
	v_readfirstlane_b32 s19, v145
	global_load_lds_dwordx4 v[140:141], off
	v_lshl_add_u64 v[140:141], s[16:17], 0, v[128:129]
	v_readfirstlane_b32 s16, v146
	s_mov_b32 m0, s16
	s_or_b32 s16, s27, 0x80
	s_mul_hi_i32 s17, s16, 0x1080
	s_mulk_i32 s16, 0x1080
	s_add_u32 s16, s8, s16
	s_addc_u32 s17, s9, s17
	global_load_lds_dwordx4 v[140:141], off
	v_lshl_add_u64 v[140:141], s[16:17], 0, v[180:181]
	s_mov_b32 m0, s19
	s_add_i32 s18, s18, 0x84000
	global_load_lds_dwordx4 v[140:141], off
	v_lshl_add_u64 v[140:141], s[16:17], 0, v[128:129]
	v_readfirstlane_b32 s16, v161
	s_mov_b32 m0, s16
	s_add_i32 s16, s26, 0x80
	s_mul_hi_i32 s17, s16, 0x1080
	s_add_u32 s16, s23, s18
	s_addc_u32 s17, s24, s17
	v_readfirstlane_b32 s18, v143
	global_load_lds_dwordx4 v[140:141], off
	v_lshl_add_u64 v[140:141], s[16:17], 0, v[180:181]
	s_mov_b32 m0, s18
	v_lshl_add_u64 v[128:129], s[16:17], 0, v[128:129]
	v_readfirstlane_b32 s16, v142
	global_load_lds_dwordx4 v[140:141], off
	s_mov_b32 m0, s16
	s_nop 0
	global_load_lds_dwordx4 v[128:129], off
	s_branch .LBB0_2558
